# indexer unit: next-unit atomic issued before the mask generation and consumed at the unit end; tie flag computed per wave from kremS/neqS (no LDS flag, two barriers fewer per unit)
# speedup vs baseline: 1.0055x; 1.0055x over previous
; #define LAS __attribute__((address_space(3)))
; __device__ __forceinline__ int fetch_item(unsigned* ctr, LAS unsigned* slot_unused) {
;     unsigned sa = (unsigned)LDS_MAIN; asm volatile("" : "+v"(sa));
;     LAS unsigned* slot = (LAS unsigned*)(uintptr_t)sa;
;     __syncthreads();
;     if (opaque_tid() == 0) *slot = atomicAdd(ctr, 1u);
;     __syncthreads();
;     return __builtin_amdgcn_readfirstlane((int)*slot);
.LBB0_646:
	s_or_b64 exec, exec, s[2:3]
	s_waitcnt vmcnt(0)
	v_readfirstlane_b32 s2, v52
	s_nop 1
	v_add_u32_e32 v2, s2, v2
	ds_write_b32 v0, v2

; #define LAS __attribute__((address_space(3)))
; __device__ __forceinline__ void sel_unit(LAS char* lds, int b, int u, const bf16_t* QI, const bf16_t* KIDX, const float* WIDX, unsigned long long* MASK) {
;     ...
;     const unsigned kstar = pref[q16]; unsigned vthr = 0u;
;     {
;         LAS unsigned* flag = (LAS unsigned*)(lds + L_FLAG);
;         const int t3 = opaque_tid();
;         if (t3 == 0) flag[0] = 0u;
;         __syncthreads();
;         if (t3 < 16 && neqS[t3] > kremS[t3]) flag[0] = 1u;
;         __syncthreads();
;         if (flag[0]) {
;             if (t3 < 16) pref[t3] = 0u;
.LBB0_753:
	ds_read_b32 v18, v60 offset:34880
	ds_read_b32 v4, v60 offset:34944
	ds_read_b32 v5, v60 offset:35008
	s_getreg_b32 s0, hwreg(HW_REG_HW_ID, 0, 6)
	s_lshl_b32 s0, s0, 2
	s_and_b32 s0, s0, 0xfc
	s_add_i32 s0, s0, 0x20040
	v_mov_b32_e32 v2, s0
	ds_read_b32 v2, v2
	s_waitcnt lgkmcnt(0)
	v_readfirstlane_b32 s0, v2
	v_mov_b32_e32 v2, v1
	s_nop 0
	v_mbcnt_lo_u32_b32 v2, -1, v2
	v_mbcnt_hi_u32_b32 v2, -1, v2
	v_lshl_or_b32 v2, s0, 6, v2
	v_cmp_gt_i32_e64 s[16:17], 16, v2
	v_cmp_gt_u32_e32 vcc, v5, v4
	s_cbranch_vccz .LBB0_1069
	s_barrier
	s_and_saveexec_b64 s[0:1], s[16:17]
	v_lshl_add_u32 v2, v2, 2, 0
	ds_write_b32 v2, v1 offset:34880
	s_or_b64 exec, exec, s[0:1]
	s_and_b32 s21, s47, 0xffffffc0
	s_mov_b64 s[16:17], -1
	s_branch .LBB0_765

; __device__ __forceinline__ void sel_unit(LAS char* lds, int b, int u, const bf16_t* QI, const bf16_t* KIDX, const float* WIDX, unsigned long long* MASK) {
;     ...
;     const int tid2 = opaque_tid(), kg2 = (tid2 & 63) >> 4; const size_t gq2 = rowbase + q0 + (tid2 & 15);
; #pragma unroll
;     for (int j = 0; j < 8; ++j) if (j < nj) {
;         const int t = SEL_TILE(j);
;         unsigned lo = 0u, hi = 0u;
; #pragma unroll
;         for (int kb = 0; kb < 4; ++kb)
; #pragma unroll
;             for (int i = 0; i < 4; ++i) { const unsigned k = sc[j][kb][i]; const unsigned kin = 16 * kb + 4 * kg2 + i;
;                 const unsigned v = 4095u - (unsigned)(64 * t + kin);
;                 const unsigned s = ((k > kstar) || (k == kstar && v >= vthr)) ? 1u : 0u;
;                 if (kb < 2) lo |= s << kin; else hi |= s << (kin - 32); __builtin_amdgcn_sched_barrier(0); }
;         { auto r = __builtin_amdgcn_permlane32_swap(lo, lo, false, false); lo = r[0] | r[1]; r = __builtin_amdgcn_permlane16_swap(lo, lo, false, false); lo = r[0] | r[1];
;           r = __builtin_amdgcn_permlane32_swap(hi, hi, false, false); hi = r[0] | r[1]; r = __builtin_amdgcn_permlane16_swap(hi, hi, false, false); hi = r[0] | r[1]; }
;         if (kg2 == 0) MASK[gq2 * 64 + t] = ((unsigned long long)hi << 32) | lo;
.LBB0_1070:
	v_cmp_eq_u32_e32 vcc, 0, v58
	s_and_saveexec_b64 s[0:1], vcc
	s_cbranch_execz .Lselq_pf_a
	v_mov_b32_e32 v52, 1
	global_atomic_add v52, v1, v52, s[58:59] offset:4 sc0
.Lselq_pf_a:
	s_or_b64 exec, exec, s[0:1]
	s_getreg_b32 s0, hwreg(HW_REG_HW_ID, 0, 6)
	s_lshl_b32 s0, s0, 2
	s_and_b32 s0, s0, 0xfc
	s_add_i32 s0, s0, 0x20040
	v_mov_b32_e32 v2, s0
	ds_read_b32 v2, v2
	s_waitcnt lgkmcnt(0)
	v_mov_b32_e32 v2, v1
	v_mov_b32_e32 v3, s53
	v_mbcnt_lo_u32_b32 v2, -1, v2
	v_mbcnt_hi_u32_b32 v2, -1, v2
	v_bfe_u32 v4, v2, 4, 2
	v_and_or_b32 v2, v2, 15, s52
	v_lshlrev_b32_e32 v20, 2, v4
	v_lshlrev_b64 v[2:3], 9, v[2:3]
	v_cmp_eq_u32_e64 s[16:17], 0, v4
	v_lshl_add_u64 v[2:3], s[68:69], 0, v[2:3]
	s_andn2_b64 vcc, exec, s[22:23]
	v_or_b32_e32 v19, 1, v20
	v_or_b32_e32 v9, 2, v20
	v_or_b32_e32 v8, 3, v20
	v_or_b32_e32 v7, 16, v20
	v_or_b32_e32 v6, 17, v20
	v_or_b32_e32 v5, 18, v20
	v_or_b32_e32 v4, 19, v20
	s_cbranch_vccnz .LBB0_1074
	s_lshl_b32 s21, s46, 6
	s_sub_i32 s21, 0xfff, s21
	v_sub_u32_e32 v21, s21, v20
	v_sub_u32_e32 v21, v21, v0
	v_cmp_gt_i32_e64 vcc, 3, v21
	v_cmp_gt_i32_e64 s[0:1], 19, v21
	v_cmp_gt_i32_e64 s[18:19], 35, v21
	v_cmp_gt_i32_e64 s[22:23], 51, v21
	v_subb_co_u32_e64 v26, vcc, v63, v18, vcc
	v_subb_co_u32_e64 v27, s[0:1], v67, v18, s[0:1]
	v_subb_co_u32_e64 v28, s[18:19], v71, v18, s[18:19]
	v_subb_co_u32_e64 v29, s[22:23], v75, v18, s[22:23]
	v_addc_co_u32_e64 v22, vcc, 0, 0, vcc
	v_addc_co_u32_e64 v23, s[0:1], 0, 0, s[0:1]
	v_addc_co_u32_e64 v24, s[18:19], 0, 0, s[18:19]
	v_addc_co_u32_e64 v25, s[22:23], 0, 0, s[22:23]
	v_cmp_gt_i32_e64 vcc, 2, v21
	v_cmp_gt_i32_e64 s[0:1], 18, v21
	v_cmp_gt_i32_e64 s[18:19], 34, v21
	v_cmp_gt_i32_e64 s[22:23], 50, v21
	v_subb_co_u32_e64 v26, vcc, v64, v18, vcc
	v_subb_co_u32_e64 v27, s[0:1], v68, v18, s[0:1]
	v_subb_co_u32_e64 v28, s[18:19], v72, v18, s[18:19]
	v_subb_co_u32_e64 v29, s[22:23], v76, v18, s[22:23]
	v_addc_co_u32_e64 v22, vcc, v22, v22, vcc
	v_addc_co_u32_e64 v23, s[0:1], v23, v23, s[0:1]
	v_addc_co_u32_e64 v24, s[18:19], v24, v24, s[18:19]
	v_addc_co_u32_e64 v25, s[22:23], v25, v25, s[22:23]
	v_cmp_gt_i32_e64 vcc, 1, v21
	v_cmp_gt_i32_e64 s[0:1], 17, v21
	v_cmp_gt_i32_e64 s[18:19], 33, v21
	v_cmp_gt_i32_e64 s[22:23], 49, v21
	v_subb_co_u32_e64 v26, vcc, v61, v18, vcc
	v_subb_co_u32_e64 v27, s[0:1], v65, v18, s[0:1]
	v_subb_co_u32_e64 v28, s[18:19], v69, v18, s[18:19]
	v_subb_co_u32_e64 v29, s[22:23], v73, v18, s[22:23]
	v_addc_co_u32_e64 v22, vcc, v22, v22, vcc
	v_addc_co_u32_e64 v23, s[0:1], v23, v23, s[0:1]
	v_addc_co_u32_e64 v24, s[18:19], v24, v24, s[18:19]
	v_addc_co_u32_e64 v25, s[22:23], v25, v25, s[22:23]
	v_cmp_gt_i32_e64 vcc, 0, v21
	v_cmp_gt_i32_e64 s[0:1], 16, v21
	v_cmp_gt_i32_e64 s[18:19], 32, v21
	v_cmp_gt_i32_e64 s[22:23], 48, v21
	v_subb_co_u32_e64 v26, vcc, v62, v18, vcc
	v_subb_co_u32_e64 v27, s[0:1], v66, v18, s[0:1]
	v_subb_co_u32_e64 v28, s[18:19], v70, v18, s[18:19]
	v_subb_co_u32_e64 v29, s[22:23], v74, v18, s[22:23]
	v_addc_co_u32_e64 v22, vcc, v22, v22, vcc
	v_addc_co_u32_e64 v23, s[0:1], v23, v23, s[0:1]
	v_addc_co_u32_e64 v24, s[18:19], v24, v24, s[18:19]
	v_addc_co_u32_e64 v25, s[22:23], v25, v25, s[22:23]
	v_lshlrev_b32_e32 v34, v20, v22
	v_lshlrev_b32_e32 v35, v20, v24
	v_lshl_or_b32 v34, v23, v7, v34
	v_lshl_or_b32 v35, v25, v7, v35
	s_nop 0
	v_mov_b32_e32 v36, v34
	v_mov_b32_e32 v37, v35
	s_nop 1
	v_permlane32_swap_b32_e32 v34, v36
	v_permlane32_swap_b32_e32 v35, v37
	v_or_b32_e32 v34, v34, v36
	v_or_b32_e32 v35, v35, v37
	v_mov_b32_e32 v36, v34
	v_mov_b32_e32 v37, v35
	s_nop 1
	v_permlane16_swap_b32_e32 v34, v36
	v_permlane16_swap_b32_e32 v35, v37
	v_or_b32_e32 v34, v34, v36
	v_or_b32_e32 v35, v35, v37
	v_not_b32_e32 v34, v34
	v_not_b32_e32 v35, v35
	s_ashr_i32 s47, s46, 31
	s_and_saveexec_b64 s[0:1], s[16:17]
	v_lshl_add_u64 v[32:33], s[46:47], 3, v[2:3]
	global_store_dwordx2 v[32:33], v[34:35], off
	s_or_b64 exec, exec, s[0:1]

; __device__ __forceinline__ void sel_unit(LAS char* lds, int b, int u, const bf16_t* QI, const bf16_t* KIDX, const float* WIDX, unsigned long long* MASK) {
;     ...
;     if (c <= 3) {
;         unsigned ones = 0xffffffffu; asm volatile("" : "+v"(ones));
;         for (int i = tid; i < 16 * (c + 1); i += 512) { unsigned* mp = (unsigned*)(MASK + (rowbase + q0 + (i & 15)) * 64 + (i >> 4)); mp[0] = ones; mp[1] = ones; }
;         return;
.LBB0_1103:
	s_and_b64 vcc, exec, s[2:3]
	s_cbranch_vccz .LBB0_1108
	v_cmp_eq_u32_e32 vcc, 0, v58
	s_and_saveexec_b64 s[0:1], vcc
	s_cbranch_execz .Lselq_pf_b
	v_mov_b32_e32 v52, 1
	global_atomic_add v52, v1, v52, s[58:59] offset:4 sc0
.Lselq_pf_b:
	s_or_b64 exec, exec, s[0:1]
	s_lshl_b32 s4, s34, 4
	s_add_i32 s4, s4, 16
	v_mov_b32_e32 v2, -1
	v_cmp_gt_i32_e32 vcc, s4, v58
	s_and_saveexec_b64 s[0:1], vcc
	s_cbranch_execz .LBB0_1107
	v_mov_b32_e32 v5, s53
	v_or_b32_e32 v4, s52, v59
	v_lshlrev_b64 v[4:5], 9, v[4:5]
	v_lshl_add_u64 v[4:5], s[68:69], 0, v[4:5]
	v_mov_b32_e32 v3, v2
	s_mov_b64 s[2:3], 0

; #define LAS __attribute__((address_space(3)))
; __device__ __forceinline__ int fetch_item(unsigned* ctr, LAS unsigned* slot_unused) {
;     unsigned sa = (unsigned)LDS_MAIN; asm volatile("" : "+v"(sa));
;     LAS unsigned* slot = (LAS unsigned*)(uintptr_t)sa;
;     __syncthreads();
;     if (opaque_tid() == 0) *slot = atomicAdd(ctr, 1u);
;     __syncthreads();
;     return __builtin_amdgcn_readfirstlane((int)*slot);
.LBB0_1108:
	v_mov_b32_e32 v0, 0x20000
	s_barrier
	s_getreg_b32 s0, hwreg(HW_REG_HW_ID, 0, 6)
	s_lshl_b32 s0, s0, 2
	s_and_b32 s0, s0, 0xfc
	s_add_i32 s0, s0, 0x20040
	v_mov_b32_e32 v2, s0
	ds_read_b32 v2, v2
	s_waitcnt lgkmcnt(0)
	v_readfirstlane_b32 s0, v2
	v_mov_b32_e32 v2, v1
	s_nop 0
	v_mbcnt_lo_u32_b32 v2, -1, v2
	v_mbcnt_hi_u32_b32 v2, -1, v2
	v_lshl_or_b32 v2, s0, 6, v2
	v_cmp_eq_u32_e32 vcc, 0, v2
	s_and_saveexec_b64 s[0:1], vcc
	s_cbranch_execz .LBB0_647
	s_mov_b64 s[4:5], exec
	v_mbcnt_lo_u32_b32 v2, s4, 0
	v_mbcnt_hi_u32_b32 v2, s5, v2
	v_cmp_eq_u32_e32 vcc, 0, v2
	s_and_saveexec_b64 s[2:3], vcc
	s_cbranch_execz .LBB0_646
	s_bcnt1_i32_b64 s4, s[4:5]
	s_branch .LBB0_646
